# DF early-half step P.V: d-block 2,3 fragment reads issued under the eight MFMAs of d-blocks 0,1 (two spare quads + freed quads)
# speedup vs baseline: 1.0016x; 1.0016x over previous
.LBB0_445:
	v_fma_f32 v109, v236, s83, -v234
	v_fmamk_f32 v0, v14, 0x3e38aa3b, v109
	v_exp_f32_e32 v110, v0
	v_fmamk_f32 v0, v186, 0x3e38aa3b, v109
	v_exp_f32_e32 v111, v0
	v_fmamk_f32 v0, v15, 0x3e38aa3b, v109
	v_exp_f32_e32 v14, v0
	v_fmamk_f32 v0, v187, 0x3e38aa3b, v109
	v_exp_f32_e32 v0, v0
	v_add_f32_e32 v15, v110, v111
	v_add_f32 v80, v14, v0
	v_add_f32 v81, v15, v1
	s_nop 0
	v_add_f32 v90, v80, v80
	v_add_f32 v91, v80, v81
	v_fmamk_f32 v80, v188, 0x3e38aa3b, v109
	v_fmamk_f32 v15, v184, 0x3e38aa3b, v109
	v_exp_f32_e32 v148, v80
	v_fmamk_f32 v80, v185, 0x3e38aa3b, v109
	v_exp_f32_e32 v15, v15
	v_exp_f32_e32 v82, v80
	v_fmamk_f32 v80, v189, 0x3e38aa3b, v109
	v_exp_f32_e32 v90, v80
	v_add_f32_e32 v83, v15, v148
	v_add_f32 v80, v82, v90
	v_add_f32 v81, v83, v91
	s_nop 0
	v_add_f32 v92, v80, v80
	v_add_f32 v93, v80, v81
	v_fmamk_f32 v80, v190, 0x3e38aa3b, v109
	v_exp_f32_e32 v83, v80
	v_fmamk_f32 v80, v192, 0x3e38aa3b, v109
	v_exp_f32_e32 v91, v80
	v_fmamk_f32 v80, v191, 0x3e38aa3b, v109
	v_exp_f32_e32 v84, v80
	v_fmamk_f32 v80, v193, 0x3e38aa3b, v109
	v_exp_f32_e32 v92, v80
	v_add_f32_e32 v85, v83, v91
	v_add_f32 v80, v84, v92
	v_add_f32 v81, v85, v93
	s_nop 0
	v_add_f32 v94, v80, v80
	v_add_f32 v95, v80, v81
	v_fmamk_f32 v80, v194, 0x3e38aa3b, v109
	v_exp_f32_e32 v85, v80
	v_fmamk_f32 v80, v198, 0x3e38aa3b, v109
	v_exp_f32_e32 v93, v80
	v_fmamk_f32 v80, v195, 0x3e38aa3b, v109
	v_exp_f32_e32 v86, v80
	v_fmamk_f32 v80, v199, 0x3e38aa3b, v109
	v_exp_f32_e32 v94, v80
	v_add_f32_e32 v87, v85, v93
	v_add_f32 v80, v86, v94
	v_add_f32 v81, v87, v95
	s_nop 0
	v_add_f32 v96, v80, v80
	v_add_f32 v97, v80, v81
	v_fmamk_f32 v80, v200, 0x3e38aa3b, v109
	v_exp_f32_e32 v87, v80
	v_fmamk_f32 v80, v202, 0x3e38aa3b, v109
	v_exp_f32_e32 v95, v80
	v_fmamk_f32 v80, v201, 0x3e38aa3b, v109
	v_exp_f32_e32 v88, v80
	v_fmamk_f32 v80, v203, 0x3e38aa3b, v109
	v_exp_f32_e32 v96, v80
	v_add_f32_e32 v89, v87, v95
	v_add_f32 v80, v88, v96
	v_add_f32 v81, v89, v97
	s_nop 0
	v_add_f32 v98, v80, v80
	v_add_f32 v99, v80, v81
	v_fmamk_f32 v80, v204, 0x3e38aa3b, v109
	v_exp_f32_e32 v89, v80
	v_fmamk_f32 v80, v206, 0x3e38aa3b, v109
	v_exp_f32_e32 v97, v80
	v_fmamk_f32 v80, v205, 0x3e38aa3b, v109
	v_exp_f32_e32 v100, v80
	v_fmamk_f32 v80, v207, 0x3e38aa3b, v109
	v_exp_f32_e32 v98, v80
	v_add_f32_e32 v101, v89, v97
	v_add_f32 v80, v100, v98
	v_add_f32 v81, v101, v99
	s_nop 0
	v_add_f32 v102, v80, v80
	v_add_f32 v103, v80, v81
	v_fmamk_f32 v80, v208, 0x3e38aa3b, v109
	v_exp_f32_e32 v99, v80
	v_fmamk_f32 v80, v210, 0x3e38aa3b, v109
	v_exp_f32_e32 v101, v80
	v_fmamk_f32 v80, v209, 0x3e38aa3b, v109
	v_exp_f32_e32 v104, v80
	v_fmamk_f32 v80, v211, 0x3e38aa3b, v109
	v_exp_f32_e32 v102, v80
	v_add_f32_e32 v105, v99, v101
	v_add_f32 v80, v104, v102
	v_add_f32 v81, v105, v103
	s_nop 0
	v_add_f32 v106, v80, v80
	v_add_f32 v107, v80, v81
	v_fmamk_f32 v80, v212, 0x3e38aa3b, v109
	v_exp_f32_e32 v103, v80
	v_fmamk_f32 v80, v214, 0x3e38aa3b, v109
	v_exp_f32_e32 v105, v80
	v_fmamk_f32 v80, v213, 0x3e38aa3b, v109
	v_fmac_f32_e32 v109, 0x3e38aa3b, v215
	v_exp_f32_e32 v108, v80
	v_exp_f32_e32 v106, v109
	v_add_f32_e32 v109, v103, v105
	v_add_f32 v80, v108, v106
	v_add_f32 v81, v109, v107
	s_nop 0
	v_add_f32_e32 v80, v80, v81
	v_add_f32_e32 v217, v217, v80
	v_cvt_pk_bf16_f32 v80, v110, v14
	v_cvt_pk_bf16_f32 v81, v15, v82
	v_cvt_pk_bf16_f32 v82, v83, v84
	v_cvt_pk_bf16_f32 v83, v85, v86
	v_cvt_pk_bf16_f32 v84, v87, v88
	v_cvt_pk_bf16_f32 v85, v89, v100
	v_cvt_pk_bf16_f32 v86, v99, v104
	v_cvt_pk_bf16_f32 v87, v103, v108
	v_cvt_pk_bf16_f32 v88, v111, v0
	v_cvt_pk_bf16_f32 v89, v148, v90
	v_cvt_pk_bf16_f32 v90, v91, v92
	v_cvt_pk_bf16_f32 v91, v93, v94
	v_cvt_pk_bf16_f32 v92, v95, v96
	v_cvt_pk_bf16_f32 v93, v97, v98
	v_cvt_pk_bf16_f32 v94, v101, v102
	v_cvt_pk_bf16_f32 v95, v105, v106
	ds_read_b64_tr_b16 v[240:241], v235 offset:8192
	ds_read_b64_tr_b16 v[242:243], v235 offset:8704
	ds_read_b64_tr_b16 v[248:249], v235 offset:12288
	ds_read_b64_tr_b16 v[250:251], v235 offset:12800
	s_waitcnt lgkmcnt(4)
	v_mfma_f32_32x32x16_bf16 v[64:79], v[6:9], v[80:83], v[64:79]
	v_mfma_f32_32x32x16_bf16 v[64:79], v[2:5], v[84:87], v[64:79]
	ds_read_b64_tr_b16 v[2:3], v235 offset:9216
	ds_read_b64_tr_b16 v[4:5], v235 offset:9728
	ds_read_b64_tr_b16 v[6:7], v235 offset:13312
	ds_read_b64_tr_b16 v[8:9], v235 offset:13824
	v_mfma_f32_32x32x16_bf16 v[64:79], v[136:139], v[88:91], v[64:79]
	v_mfma_f32_32x32x16_bf16 v[64:79], v[10:13], v[92:95], v[64:79]
	ds_read_b64_tr_b16 v[136:137], v235 offset:10240
	ds_read_b64_tr_b16 v[138:139], v235 offset:10752
	ds_read_b64_tr_b16 v[10:11], v235 offset:14336
	ds_read_b64_tr_b16 v[12:13], v235 offset:14848
	v_mfma_f32_32x32x16_bf16 v[48:63], v[140:143], v[80:83], v[48:63]
	v_mfma_f32_32x32x16_bf16 v[48:63], v[128:131], v[84:87], v[48:63]
	ds_read_b64_tr_b16 v[140:141], v235 offset:11264
	ds_read_b64_tr_b16 v[142:143], v235 offset:11776
	ds_read_b64_tr_b16 v[128:129], v235 offset:15360
	ds_read_b64_tr_b16 v[130:131], v235 offset:15872
	v_mfma_f32_32x32x16_bf16 v[48:63], v[144:147], v[88:91], v[48:63]
	v_mfma_f32_32x32x16_bf16 v[48:63], v[132:135], v[92:95], v[48:63]
	s_waitcnt lgkmcnt(12)
	v_mfma_f32_32x32x16_bf16 v[32:47], v[240:243], v[80:83], v[32:47]
	v_mfma_f32_32x32x16_bf16 v[16:31], v[248:251], v[80:83], v[16:31]
	s_waitcnt lgkmcnt(8)
	v_mfma_f32_32x32x16_bf16 v[32:47], v[2:5], v[84:87], v[32:47]
	v_mfma_f32_32x32x16_bf16 v[16:31], v[6:9], v[84:87], v[16:31]
	s_waitcnt lgkmcnt(4)
	v_mfma_f32_32x32x16_bf16 v[32:47], v[136:139], v[88:91], v[32:47]
	v_mfma_f32_32x32x16_bf16 v[16:31], v[10:13], v[88:91], v[16:31]
	s_waitcnt lgkmcnt(0)
	v_mfma_f32_32x32x16_bf16 v[32:47], v[140:143], v[92:95], v[32:47]
	v_mfma_f32_32x32x16_bf16 v[16:31], v[128:131], v[92:95], v[16:31]
